# v20 = v18 + ktime<2> FMA loop with LDS operand reads software-pipelined 4 steps ahead (operands in v56-v119, lgkmcnt(6) per step instead of lgkmcnt(0))
# baseline (speedup 1.0000x reference)
.LBB0_619:
	v_add_u32_e32 v31, s6, v43
	ds_read_b128 v[56:59], v30
	ds_read_b128 v[60:63], v31
	ds_read_b128 v[64:67], v30 offset:528
	ds_read_b128 v[68:71], v31 offset:256
	ds_read_b128 v[72:75], v30 offset:1056
	ds_read_b128 v[76:79], v31 offset:512
	ds_read_b128 v[80:83], v30 offset:1584
	ds_read_b128 v[84:87], v31 offset:768
	s_waitcnt lgkmcnt(6)
	s_addk_i32 s6, 0x800
	s_cmpk_eq_i32 s6, 0x4000
	v_pk_fma_f32 v[14:15], v[58:59], v[60:61], v[14:15] op_sel_hi:[1,0,1]
	v_pk_fma_f32 v[12:13], v[56:57], v[60:61], v[12:13] op_sel_hi:[1,0,1]
	v_pk_fma_f32 v[10:11], v[58:59], v[60:61], v[10:11] op_sel:[0,1,0]
	v_pk_fma_f32 v[8:9], v[56:57], v[60:61], v[8:9] op_sel:[0,1,0]
	v_pk_fma_f32 v[50:51], v[56:57], v[62:63], v[4:5] op_sel_hi:[1,0,1]
	v_mov_b32_e32 v4, v63
	v_pk_fma_f32 v[32:33], v[58:59], v[62:63], v[6:7] op_sel_hi:[1,0,1]
	v_pk_fma_f32 v[48:49], v[58:59], v[4:5], v[2:3] op_sel_hi:[1,0,1]
	v_pk_fma_f32 v[46:47], v[56:57], v[4:5], v[0:1] op_sel_hi:[1,0,1]
	ds_read_b128 v[88:91], v30 offset:2112
	ds_read_b128 v[92:95], v31 offset:1024
	s_waitcnt lgkmcnt(6)
	v_pk_fma_f32 v[14:15], v[66:67], v[68:69], v[14:15] op_sel_hi:[1,0,1]
	v_pk_fma_f32 v[12:13], v[64:65], v[68:69], v[12:13] op_sel_hi:[1,0,1]
	v_pk_fma_f32 v[10:11], v[66:67], v[68:69], v[10:11] op_sel:[0,1,0]
	v_pk_fma_f32 v[8:9], v[64:65], v[68:69], v[8:9] op_sel:[0,1,0]
	v_mov_b32_e32 v68, v71
	v_pk_fma_f32 v[32:33], v[66:67], v[70:71], v[32:33] op_sel_hi:[1,0,1]
	v_pk_fma_f32 v[50:51], v[64:65], v[70:71], v[50:51] op_sel_hi:[1,0,1]
	v_pk_fma_f32 v[48:49], v[66:67], v[68:69], v[48:49] op_sel_hi:[1,0,1]
	v_pk_fma_f32 v[46:47], v[64:65], v[68:69], v[46:47] op_sel_hi:[1,0,1]
	ds_read_b128 v[96:99], v30 offset:2640
	ds_read_b128 v[100:103], v31 offset:1280
	s_waitcnt lgkmcnt(6)
	v_pk_fma_f32 v[14:15], v[74:75], v[76:77], v[14:15] op_sel_hi:[1,0,1]
	v_pk_fma_f32 v[12:13], v[72:73], v[76:77], v[12:13] op_sel_hi:[1,0,1]
	v_pk_fma_f32 v[10:11], v[74:75], v[76:77], v[10:11] op_sel:[0,1,0]
	v_pk_fma_f32 v[8:9], v[72:73], v[76:77], v[8:9] op_sel:[0,1,0]
	v_mov_b32_e32 v76, v79
	v_pk_fma_f32 v[32:33], v[74:75], v[78:79], v[32:33] op_sel_hi:[1,0,1]
	v_pk_fma_f32 v[50:51], v[72:73], v[78:79], v[50:51] op_sel_hi:[1,0,1]
	v_pk_fma_f32 v[48:49], v[74:75], v[76:77], v[48:49] op_sel_hi:[1,0,1]
	v_pk_fma_f32 v[46:47], v[72:73], v[76:77], v[46:47] op_sel_hi:[1,0,1]
	ds_read_b128 v[104:107], v30 offset:3168
	ds_read_b128 v[108:111], v31 offset:1536
	s_waitcnt lgkmcnt(6)
	v_pk_fma_f32 v[14:15], v[82:83], v[84:85], v[14:15] op_sel_hi:[1,0,1]
	v_pk_fma_f32 v[12:13], v[80:81], v[84:85], v[12:13] op_sel_hi:[1,0,1]
	v_pk_fma_f32 v[10:11], v[82:83], v[84:85], v[10:11] op_sel:[0,1,0]
	v_pk_fma_f32 v[8:9], v[80:81], v[84:85], v[8:9] op_sel:[0,1,0]
	v_mov_b32_e32 v84, v87
	v_pk_fma_f32 v[32:33], v[82:83], v[86:87], v[32:33] op_sel_hi:[1,0,1]
	v_pk_fma_f32 v[50:51], v[80:81], v[86:87], v[50:51] op_sel_hi:[1,0,1]
	v_pk_fma_f32 v[48:49], v[82:83], v[84:85], v[48:49] op_sel_hi:[1,0,1]
	v_pk_fma_f32 v[46:47], v[80:81], v[84:85], v[46:47] op_sel_hi:[1,0,1]
	ds_read_b128 v[112:115], v30 offset:3696
	ds_read_b128 v[116:119], v31 offset:1792
	s_waitcnt lgkmcnt(6)
	v_pk_fma_f32 v[14:15], v[90:91], v[92:93], v[14:15] op_sel_hi:[1,0,1]
	v_pk_fma_f32 v[12:13], v[88:89], v[92:93], v[12:13] op_sel_hi:[1,0,1]
	v_pk_fma_f32 v[10:11], v[90:91], v[92:93], v[10:11] op_sel:[0,1,0]
	v_pk_fma_f32 v[8:9], v[88:89], v[92:93], v[8:9] op_sel:[0,1,0]
	v_mov_b32_e32 v92, v95
	v_pk_fma_f32 v[32:33], v[90:91], v[94:95], v[32:33] op_sel_hi:[1,0,1]
	v_pk_fma_f32 v[50:51], v[88:89], v[94:95], v[50:51] op_sel_hi:[1,0,1]
	v_pk_fma_f32 v[48:49], v[90:91], v[92:93], v[48:49] op_sel_hi:[1,0,1]
	v_pk_fma_f32 v[46:47], v[88:89], v[92:93], v[46:47] op_sel_hi:[1,0,1]
	s_waitcnt lgkmcnt(4)
	v_pk_fma_f32 v[14:15], v[98:99], v[100:101], v[14:15] op_sel_hi:[1,0,1]
	v_pk_fma_f32 v[12:13], v[96:97], v[100:101], v[12:13] op_sel_hi:[1,0,1]
	v_pk_fma_f32 v[10:11], v[98:99], v[100:101], v[10:11] op_sel:[0,1,0]
	v_pk_fma_f32 v[8:9], v[96:97], v[100:101], v[8:9] op_sel:[0,1,0]
	v_mov_b32_e32 v100, v103
	v_pk_fma_f32 v[32:33], v[98:99], v[102:103], v[32:33] op_sel_hi:[1,0,1]
	v_pk_fma_f32 v[50:51], v[96:97], v[102:103], v[50:51] op_sel_hi:[1,0,1]
	v_pk_fma_f32 v[48:49], v[98:99], v[100:101], v[48:49] op_sel_hi:[1,0,1]
	v_pk_fma_f32 v[46:47], v[96:97], v[100:101], v[46:47] op_sel_hi:[1,0,1]
	s_waitcnt lgkmcnt(2)
	v_pk_fma_f32 v[32:33], v[106:107], v[110:111], v[32:33] op_sel_hi:[1,0,1]
	v_pk_fma_f32 v[50:51], v[104:105], v[110:111], v[50:51] op_sel_hi:[1,0,1]
	v_mov_b32_e32 v110, v111
	v_pk_fma_f32 v[14:15], v[106:107], v[108:109], v[14:15] op_sel_hi:[1,0,1]
	v_pk_fma_f32 v[12:13], v[104:105], v[108:109], v[12:13] op_sel_hi:[1,0,1]
	v_pk_fma_f32 v[10:11], v[106:107], v[108:109], v[10:11] op_sel:[0,1,0]
	v_pk_fma_f32 v[4:5], v[104:105], v[108:109], v[8:9] op_sel:[0,1,0]
	v_pk_fma_f32 v[52:53], v[106:107], v[110:111], v[48:49] op_sel_hi:[1,0,1]
	v_pk_fma_f32 v[54:55], v[104:105], v[110:111], v[46:47] op_sel_hi:[1,0,1]
	s_waitcnt lgkmcnt(0)
	v_add_u32_e32 v30, 0x1080, v30
	v_pk_fma_f32 v[6:7], v[114:115], v[118:119], v[32:33] op_sel_hi:[1,0,1]
	v_mov_b32_e32 v32, v119
	v_pk_fma_f32 v[14:15], v[114:115], v[116:117], v[14:15] op_sel_hi:[1,0,1]
	v_pk_fma_f32 v[12:13], v[112:113], v[116:117], v[12:13] op_sel_hi:[1,0,1]
	v_pk_fma_f32 v[10:11], v[114:115], v[116:117], v[10:11] op_sel:[0,1,0]
	v_pk_fma_f32 v[8:9], v[112:113], v[116:117], v[4:5] op_sel:[0,1,0]
	v_pk_fma_f32 v[4:5], v[112:113], v[118:119], v[50:51] op_sel_hi:[1,0,1]
	v_pk_fma_f32 v[2:3], v[114:115], v[32:33], v[52:53] op_sel_hi:[1,0,1]
	v_pk_fma_f32 v[0:1], v[112:113], v[32:33], v[54:55] op_sel_hi:[1,0,1]
	s_cbranch_scc0 .LBB0_619
	v_or_b32_e32 v46, s42, v21
	v_cvt_f32_i32_e32 v31, v46
	v_add_u32_e32 v30, s2, v35
	v_and_b32_e32 v30, 0x3fc, v30
	v_div_scale_f32 v32, s[6:7], s33, s33, v31
	v_rcp_f32_e32 v33, v32
	s_barrier
	s_cmpk_lt_u32 s3, 0x400
	v_fma_f32 v47, -v32, v33, 1.0
	v_fmac_f32_e32 v33, v47, v33
	v_div_scale_f32 v47, vcc, v31, s33, v31
	v_mul_f32_e32 v48, v47, v33
	v_fma_f32 v49, -v32, v48, v47
	v_fmac_f32_e32 v48, v49, v33
	v_fma_f32 v32, -v32, v48, v47
	v_div_fmas_f32 v32, v32, v33, v48
	v_div_fixup_f32 v31, v32, s33, v31
	v_cvt_f32_u32_e32 v32, v30
	v_fmamk_f32 v47, v32, 0x3c44ade8, v193
	v_mul_f32_e64 v32, v31, |v47|
	v_mul_f32_e32 v33, 0x3fb8aa3b, v32
	v_fma_f32 v48, v32, s78, -v33
	v_rndne_f32_e32 v49, v33
	v_fmac_f32_e32 v48, 0x32a5705f, v32
	v_sub_f32_e32 v33, v33, v49
	v_add_f32_e32 v33, v33, v48
	v_exp_f32_e32 v33, v33
	v_cvt_i32_f32_e32 v48, v49
	v_cmp_ngt_f32_e32 vcc, s79, v32
	v_ldexp_f32 v33, v33, v48
	s_nop 0
	v_cndmask_b32_e32 v33, 0, v33, vcc
	v_cmp_nlt_f32_e32 vcc, s80, v32
	v_or_b32_e32 v32, 1, v46
	v_cvt_f32_i32_e32 v32, v32
	v_cndmask_b32_e32 v48, v244, v33, vcc
	v_div_scale_f32 v33, s[6:7], s33, s33, v32
	v_rcp_f32_e32 v49, v33
	s_nop 0
	v_fma_f32 v50, -v33, v49, 1.0
	v_fmac_f32_e32 v49, v50, v49
	v_div_scale_f32 v50, vcc, v32, s33, v32
	v_mul_f32_e32 v51, v50, v49
	v_fma_f32 v52, -v33, v51, v50
	v_fmac_f32_e32 v51, v52, v49
	v_fma_f32 v33, -v33, v51, v50
	v_div_fmas_f32 v33, v33, v49, v51
	v_div_fixup_f32 v32, v33, s33, v32
	v_mul_f32_e64 v33, v32, |v47|
	v_mul_f32_e32 v49, 0x3fb8aa3b, v33
	v_fma_f32 v50, v33, s78, -v49
	v_rndne_f32_e32 v51, v49
	v_fmac_f32_e32 v50, 0x32a5705f, v33
	v_sub_f32_e32 v49, v49, v51
	v_add_f32_e32 v49, v49, v50
	v_exp_f32_e32 v49, v49
	v_cvt_i32_f32_e32 v50, v51
	v_cmp_ngt_f32_e32 vcc, s79, v33
	v_ldexp_f32 v49, v49, v50
	s_nop 0
	v_cndmask_b32_e32 v49, 0, v49, vcc
	v_cmp_nlt_f32_e32 vcc, s80, v33
	v_or_b32_e32 v33, 2, v46
	v_cvt_f32_i32_e32 v33, v33
	v_cndmask_b32_e32 v49, v244, v49, vcc
	v_or_b32_e32 v46, 3, v46
	v_cvt_f32_i32_e32 v46, v46
	v_div_scale_f32 v50, s[6:7], s33, s33, v33
	v_rcp_f32_e32 v51, v50
	v_pk_mul_f32 v[12:13], v[48:49], v[12:13]
	v_fma_f32 v52, -v50, v51, 1.0
	v_fmac_f32_e32 v51, v52, v51
	v_div_scale_f32 v52, vcc, v33, s33, v33
	v_mul_f32_e32 v53, v52, v51
	v_fma_f32 v54, -v50, v53, v52
	v_fmac_f32_e32 v53, v54, v51
	v_fma_f32 v50, -v50, v53, v52
	v_div_fmas_f32 v50, v50, v51, v53
	v_div_fixup_f32 v33, v50, s33, v33
	v_mul_f32_e64 v50, v33, |v47|
	v_mul_f32_e32 v51, 0x3fb8aa3b, v50
	v_fma_f32 v52, v50, s78, -v51
	v_rndne_f32_e32 v53, v51
	v_fmac_f32_e32 v52, 0x32a5705f, v50
	v_sub_f32_e32 v51, v51, v53
	v_add_f32_e32 v51, v51, v52
	v_exp_f32_e32 v51, v51
	v_cvt_i32_f32_e32 v52, v53
	v_cmp_ngt_f32_e32 vcc, s79, v50
	v_ldexp_f32 v51, v51, v52
	s_nop 0
	v_cndmask_b32_e32 v51, 0, v51, vcc
	v_cmp_nlt_f32_e32 vcc, s80, v50
	s_nop 1
	v_cndmask_b32_e32 v50, v244, v51, vcc
	v_div_scale_f32 v51, s[6:7], s33, s33, v46
	v_rcp_f32_e32 v52, v51
	s_nop 0
	v_fma_f32 v53, -v51, v52, 1.0
	v_fmac_f32_e32 v52, v53, v52
	v_div_scale_f32 v53, vcc, v46, s33, v46
	v_mul_f32_e32 v54, v53, v52
	v_fma_f32 v55, -v51, v54, v53
	v_fmac_f32_e32 v54, v55, v52
	v_fma_f32 v51, -v51, v54, v53
	v_div_fmas_f32 v51, v51, v52, v54
	v_div_fixup_f32 v46, v51, s33, v46
	v_mul_f32_e64 v47, v46, |v47|
	v_mul_f32_e32 v51, 0x3fb8aa3b, v47
	v_fma_f32 v52, v47, s78, -v51
	v_rndne_f32_e32 v53, v51
	v_fmac_f32_e32 v52, 0x32a5705f, v47
	v_sub_f32_e32 v51, v51, v53
	v_add_f32_e32 v51, v51, v52
	v_exp_f32_e32 v51, v51
	v_cvt_i32_f32_e32 v52, v53
	v_cmp_ngt_f32_e32 vcc, s79, v47
	v_ldexp_f32 v51, v51, v52
	s_nop 0
	v_cndmask_b32_e32 v51, 0, v51, vcc
	v_cmp_nlt_f32_e32 vcc, s80, v47
	s_nop 1
	v_cndmask_b32_e32 v51, v244, v51, vcc
	v_pk_mul_f32 v[14:15], v[50:51], v[14:15]
	ds_write_b128 v44, v[12:15]
	v_or_b32_e32 v12, 1, v30
	v_cvt_f32_u32_e32 v12, v12
	v_fmamk_f32 v15, v12, 0x3c44ade8, v193
	v_mul_f32_e64 v12, v31, |v15|
	v_mul_f32_e32 v13, 0x3fb8aa3b, v12
	v_fma_f32 v14, v12, s78, -v13
	v_rndne_f32_e32 v47, v13
	v_fmac_f32_e32 v14, 0x32a5705f, v12
	v_sub_f32_e32 v13, v13, v47
	v_add_f32_e32 v13, v13, v14
	v_exp_f32_e32 v13, v13
	v_cvt_i32_f32_e32 v14, v47
	v_cmp_ngt_f32_e32 vcc, s79, v12
	v_ldexp_f32 v13, v13, v14
	s_nop 0
	v_cndmask_b32_e32 v13, 0, v13, vcc
	v_cmp_nlt_f32_e32 vcc, s80, v12
	s_nop 1
	v_cndmask_b32_e32 v12, v244, v13, vcc
	v_mul_f32_e64 v13, v32, |v15|
	v_mul_f32_e32 v14, 0x3fb8aa3b, v13
	v_fma_f32 v47, v13, s78, -v14
	v_rndne_f32_e32 v48, v14
	v_fmac_f32_e32 v47, 0x32a5705f, v13
	v_sub_f32_e32 v14, v14, v48
	v_add_f32_e32 v14, v14, v47
	v_exp_f32_e32 v14, v14
	v_cvt_i32_f32_e32 v47, v48
	v_cmp_ngt_f32_e32 vcc, s79, v13
	v_ldexp_f32 v14, v14, v47
	s_nop 0
	v_cndmask_b32_e32 v14, 0, v14, vcc
	v_cmp_nlt_f32_e32 vcc, s80, v13
	s_nop 1
	v_cndmask_b32_e32 v13, v244, v14, vcc
	v_mul_f32_e64 v14, v33, |v15|
	v_mul_f32_e32 v47, 0x3fb8aa3b, v14
	v_fma_f32 v48, v14, s78, -v47
	v_rndne_f32_e32 v49, v47
	v_fmac_f32_e32 v48, 0x32a5705f, v14
	v_sub_f32_e32 v47, v47, v49
	v_add_f32_e32 v47, v47, v48
	v_exp_f32_e32 v47, v47
	v_cvt_i32_f32_e32 v48, v49
	v_cmp_ngt_f32_e32 vcc, s79, v14
	v_mul_f32_e64 v15, v46, |v15|
	v_pk_mul_f32 v[8:9], v[12:13], v[8:9]
	v_ldexp_f32 v47, v47, v48
	v_cndmask_b32_e32 v47, 0, v47, vcc
	v_cmp_nlt_f32_e32 vcc, s80, v14
	s_nop 1
	v_cndmask_b32_e32 v14, v244, v47, vcc
	v_mul_f32_e32 v47, 0x3fb8aa3b, v15
	v_fma_f32 v48, v15, s78, -v47
	v_rndne_f32_e32 v49, v47
	v_fmac_f32_e32 v48, 0x32a5705f, v15
	v_sub_f32_e32 v47, v47, v49
	v_add_f32_e32 v47, v47, v48
	v_exp_f32_e32 v47, v47
	v_cvt_i32_f32_e32 v48, v49
	v_cmp_ngt_f32_e32 vcc, s79, v15
	v_ldexp_f32 v47, v47, v48
	s_nop 0
	v_cndmask_b32_e32 v47, 0, v47, vcc
	v_cmp_nlt_f32_e32 vcc, s80, v15
	s_nop 1
	v_cndmask_b32_e32 v15, v244, v47, vcc
	v_pk_mul_f32 v[10:11], v[14:15], v[10:11]
	ds_write_b128 v44, v[8:11] offset:528
	v_or_b32_e32 v8, 2, v30
	v_cvt_f32_u32_e32 v8, v8
	v_fmamk_f32 v11, v8, 0x3c44ade8, v193
	v_mul_f32_e64 v8, v31, |v11|
	v_mul_f32_e32 v9, 0x3fb8aa3b, v8
	v_fma_f32 v10, v8, s78, -v9
	v_rndne_f32_e32 v12, v9
	v_fmac_f32_e32 v10, 0x32a5705f, v8
	v_sub_f32_e32 v9, v9, v12
	v_add_f32_e32 v9, v9, v10
	v_exp_f32_e32 v9, v9
	v_cvt_i32_f32_e32 v10, v12
	v_cmp_ngt_f32_e32 vcc, s79, v8
	v_ldexp_f32 v9, v9, v10
	s_nop 0
	v_cndmask_b32_e32 v9, 0, v9, vcc
	v_cmp_nlt_f32_e32 vcc, s80, v8
	s_nop 1
	v_cndmask_b32_e32 v8, v244, v9, vcc
	v_mul_f32_e64 v9, v32, |v11|
	v_mul_f32_e32 v10, 0x3fb8aa3b, v9
	v_fma_f32 v12, v9, s78, -v10
	v_rndne_f32_e32 v13, v10
	v_fmac_f32_e32 v12, 0x32a5705f, v9
	v_sub_f32_e32 v10, v10, v13
	v_add_f32_e32 v10, v10, v12
	v_exp_f32_e32 v10, v10
	v_cvt_i32_f32_e32 v12, v13
	v_cmp_ngt_f32_e32 vcc, s79, v9
	v_ldexp_f32 v10, v10, v12
	s_nop 0
	v_cndmask_b32_e32 v10, 0, v10, vcc
	v_cmp_nlt_f32_e32 vcc, s80, v9
	s_nop 1
	v_cndmask_b32_e32 v9, v244, v10, vcc
	v_mul_f32_e64 v10, v33, |v11|
	v_mul_f32_e32 v12, 0x3fb8aa3b, v10
	v_fma_f32 v13, v10, s78, -v12
	v_rndne_f32_e32 v14, v12
	v_fmac_f32_e32 v13, 0x32a5705f, v10
	v_sub_f32_e32 v12, v12, v14
	v_add_f32_e32 v12, v12, v13
	v_exp_f32_e32 v12, v12
	v_cvt_i32_f32_e32 v13, v14
	v_cmp_ngt_f32_e32 vcc, s79, v10
	v_mul_f32_e64 v11, v46, |v11|
	v_pk_mul_f32 v[4:5], v[8:9], v[4:5]
	v_ldexp_f32 v12, v12, v13
	v_cndmask_b32_e32 v12, 0, v12, vcc
	v_cmp_nlt_f32_e32 vcc, s80, v10
	s_nop 1
	v_cndmask_b32_e32 v10, v244, v12, vcc
	v_mul_f32_e32 v12, 0x3fb8aa3b, v11
	v_fma_f32 v13, v11, s78, -v12
	v_rndne_f32_e32 v14, v12
	v_fmac_f32_e32 v13, 0x32a5705f, v11
	v_sub_f32_e32 v12, v12, v14
	v_add_f32_e32 v12, v12, v13
	v_exp_f32_e32 v12, v12
	v_cvt_i32_f32_e32 v13, v14
	v_cmp_ngt_f32_e32 vcc, s79, v11
	v_ldexp_f32 v12, v12, v13
	s_nop 0
	v_cndmask_b32_e32 v12, 0, v12, vcc
	v_cmp_nlt_f32_e32 vcc, s80, v11
	s_nop 1
	v_cndmask_b32_e32 v11, v244, v12, vcc
	v_pk_mul_f32 v[6:7], v[10:11], v[6:7]
	ds_write_b128 v44, v[4:7] offset:1056
	v_or_b32_e32 v4, 3, v30
	v_cvt_f32_u32_e32 v4, v4
	v_add_lshl_u32 v30, s2, v34, 16
	v_and_b32_e32 v194, 0x3ff0000, v30
	s_mov_b64 s[2:3], -1
	v_fmamk_f32 v7, v4, 0x3c44ade8, v193
	v_mul_f32_e64 v4, v31, |v7|
	v_mul_f32_e32 v5, 0x3fb8aa3b, v4
	v_fma_f32 v6, v4, s78, -v5
	v_rndne_f32_e32 v8, v5
	v_fmac_f32_e32 v6, 0x32a5705f, v4
	v_sub_f32_e32 v5, v5, v8
	v_add_f32_e32 v5, v5, v6
	v_exp_f32_e32 v5, v5
	v_cvt_i32_f32_e32 v6, v8
	v_cmp_ngt_f32_e32 vcc, s79, v4
	v_ldexp_f32 v5, v5, v6
	s_nop 0
	v_cndmask_b32_e32 v5, 0, v5, vcc
	v_cmp_nlt_f32_e32 vcc, s80, v4
	s_nop 1
	v_cndmask_b32_e32 v4, v244, v5, vcc
	v_mul_f32_e64 v5, v32, |v7|
	v_mul_f32_e32 v6, 0x3fb8aa3b, v5
	v_fma_f32 v8, v5, s78, -v6
	v_rndne_f32_e32 v9, v6
	v_fmac_f32_e32 v8, 0x32a5705f, v5
	v_sub_f32_e32 v6, v6, v9
	v_add_f32_e32 v6, v6, v8
	v_exp_f32_e32 v6, v6
	v_cvt_i32_f32_e32 v8, v9
	v_cmp_ngt_f32_e32 vcc, s79, v5
	v_ldexp_f32 v6, v6, v8
	s_nop 0
	v_cndmask_b32_e32 v6, 0, v6, vcc
	v_cmp_nlt_f32_e32 vcc, s80, v5
	s_nop 1
	v_cndmask_b32_e32 v5, v244, v6, vcc
	v_mul_f32_e64 v6, v33, |v7|
	v_mul_f32_e32 v8, 0x3fb8aa3b, v6
	v_fma_f32 v9, v6, s78, -v8
	v_rndne_f32_e32 v10, v8
	v_fmac_f32_e32 v9, 0x32a5705f, v6
	v_sub_f32_e32 v8, v8, v10
	v_add_f32_e32 v8, v8, v9
	v_exp_f32_e32 v8, v8
	v_cvt_i32_f32_e32 v9, v10
	v_cmp_ngt_f32_e32 vcc, s79, v6
	v_mul_f32_e64 v7, v46, |v7|
	v_pk_mul_f32 v[0:1], v[4:5], v[0:1]
	v_ldexp_f32 v8, v8, v9
	v_cndmask_b32_e32 v8, 0, v8, vcc
	v_cmp_nlt_f32_e32 vcc, s80, v6
	v_lshl_add_u64 v[32:33], s[40:41], 0, v[194:195]
	s_nop 0
	v_cndmask_b32_e32 v6, v244, v8, vcc
	v_mul_f32_e32 v8, 0x3fb8aa3b, v7
	v_fma_f32 v9, v7, s78, -v8
	v_rndne_f32_e32 v10, v8
	v_fmac_f32_e32 v9, 0x32a5705f, v7
	v_sub_f32_e32 v8, v8, v10
	v_add_f32_e32 v8, v8, v9
	v_exp_f32_e32 v8, v8
	v_cvt_i32_f32_e32 v9, v10
	v_cmp_ngt_f32_e32 vcc, s79, v7
	v_ldexp_f32 v8, v8, v9
	s_nop 0
	v_cndmask_b32_e32 v8, 0, v8, vcc
	v_cmp_nlt_f32_e32 vcc, s80, v7
	s_nop 1
	v_cndmask_b32_e32 v7, v244, v8, vcc
	v_pk_mul_f32 v[2:3], v[6:7], v[2:3]
	ds_write_b128 v45, v[0:3]
	s_waitcnt lgkmcnt(0)
	s_barrier
	ds_read_b128 v[0:3], v37
	ds_read_b128 v[4:7], v37 offset:16
	ds_read_b128 v[8:11], v37 offset:32
	ds_read_b128 v[12:15], v37 offset:48
	s_cbranch_scc0 .LBB0_622
	s_ashr_i32 s43, s42, 31
	v_lshl_add_u64 v[30:31], s[42:43], 2, v[32:33]
	v_lshlrev_b32_e32 v194, 2, v20
	v_lshl_add_u64 v[30:31], v[30:31], 0, v[194:195]
	s_waitcnt lgkmcnt(3)
	global_store_dwordx4 v[30:31], v[0:3], off
	s_waitcnt lgkmcnt(2)
	global_store_dwordx4 v[30:31], v[4:7], off offset:16
	s_waitcnt lgkmcnt(1)
	global_store_dwordx4 v[30:31], v[8:11], off offset:32
	s_cbranch_execnz .LBB0_617
	s_branch .LBB0_623
